# attention: queue pop issued one unit early (atomic latency hidden); combine loop with all loads in flight; lean GEMM1 epilogue
# baseline (speedup 1.0000x reference)
; __global__ void __launch_bounds__(NTHR, 2) fwd_kernel(Args args) {
;     ...
;                         int tl = F.tid; asm volatile("" : "+v"(tl));
;                         const bool first = ((u - NR1) & 1) == 0;
;                         if (tl == 0 && !first) *bc = NR1 + 2 * (atomicAdd(ctr + rep, 1u) - NR1);
;                         attn_stage(F.lds, tl, st);
;                         __syncthreads();
;                         const int un = first ? u + 1 : (int)*bc;
.LBB0_469:
	v_mov_b32_e32 v64, v133
	s_bitcmp1_b32 s13, 0
	s_cselect_b64 s[18:19], -1, 0
	v_cmp_eq_u32_e32 vcc, 0, v64
	s_and_b64 s[14:15], s[18:19], vcc
	s_and_saveexec_b64 s[20:21], s[14:15]
	s_cbranch_execz .LBB0_473
	s_mov_b64 s[24:25], exec
	v_mbcnt_lo_u32_b32 v0, s24, 0
	v_mbcnt_hi_u32_b32 v0, s25, v0
	v_cmp_eq_u32_e32 vcc, 0, v0
	s_and_saveexec_b64 s[22:23], vcc
	s_cbranch_execz .LBB0_472
	s_waitcnt vmcnt(0)
	v_mov_b32_e32 v2, v250

; __global__ void __launch_bounds__(NTHR, 2) fwd_kernel(Args args) {
;     ...
;                         if (tl == 0 && !first) *bc = NR1 + 2 * (atomicAdd(ctr + rep, 1u) - NR1);
;                         attn_stage(F.lds, tl, st);
;                         __syncthreads();
;                         const int un = first ? u + 1 : (int)*bc;
;                         attn_rotary(F.lds, tl, rc);
;                         if (un < UEND) attn_load(tl, un - NR1, Pb, ropeA, st, rc);
.LBB0_504:
	s_or_b32 s5, s13, 1
	v_cmp_eq_u32_e32 vcc, 0, v64
	s_and_saveexec_b64 s[14:15], vcc
	s_cbranch_execz .Lattnq_skip
	v_mov_b32_e32 v250, 1
	global_atomic_add v250, v1, v250, s[16:17] sc0
.Lattnq_skip:
	s_or_b64 exec, exec, s[14:15]
	s_movk_i32 s14, 0x180
	v_cmp_gt_i32_e64 s[38:39], s14, v64
	s_and_saveexec_b64 s[18:19], s[38:39]
	s_cbranch_execnz .LBB0_476
	s_branch .LBB0_477

; __device__ __forceinline__ void combine_rows(const Frame& F, int r0, int r1, const bf16* P, const float* LSE, bf16* COMB) {
;     const int lane = F.lane, h = lane >> 3;
;     for (int row = r0 + F.wave; row < r1; row += NWAVES) {
;         const float l0 = LSE[(size_t)row * 24 + h], l1 = LSE[(size_t)row * 24 + 8 + h], l2 = LSE[(size_t)row * 24 + 16 + h];
;         const float mx = fmaxf(l0, fmaxf(l1, l2));
;         float e0 = __builtin_amdgcn_exp2f((l0 - mx) * 1.4426950408889634f), e1 = __builtin_amdgcn_exp2f((l1 - mx) * 1.4426950408889634f), e2 = __builtin_amdgcn_exp2f((l2 - mx) * 1.4426950408889634f);
;         const float inv = 1.0f / (e0 + e1 + e2); e0 *= inv; e1 *= inv; e2 *= inv;
;         const int bl = row >> 12, t = row & 4095, ch = lane & 7;
;         const bf16* hb = P + PL_A + ((size_t)(bl * 3 * 24 + h) * 4096) * 64 + ch * 8;
;         const u32x4 a = *(const u32x4*)(hb + (size_t)t * 64), b = *(const u32x4*)(hb + ((size_t)8 * 4096 + ((t & 3) << 10) + (t >> 2)) * 64), c = *(const u32x4*)(hb + ((size_t)16 * 4096 + ((t & 15) << 8) + (t >> 4)) * 64);
.LBB0_647:
	s_or_b64 exec, exec, s[0:1]
	s_waitcnt lgkmcnt(0)
	v_mov_b32_e32 v3, s31
	s_waitcnt lgkmcnt(0)
	s_barrier
	ds_read_b32 v3, v3
	s_movk_i32 s0, 0xff
	s_waitcnt lgkmcnt(0)
	v_cmp_lt_i32_e32 vcc, s0, v3
	v_readfirstlane_b32 s5, v3
	s_mov_b64 s[0:1], -1
	s_cbranch_vccnz .LBB0_642
	v_readlane_b32 s0, v255, 14
	v_readlane_b32 s1, v255, 15
	s_andn2_b64 vcc, exec, s[0:1]
	s_cbranch_vccnz .LBB0_641
	s_lshl_b32 s14, s5, 6
	v_readlane_b32 s20, v255, 22
	s_lshl_b32 s1, s5, 14
	v_readlane_b32 s15, v255, 21
	s_or_b32 s13, s14, s20
	s_or_b32 s0, s14, 56
	s_add_i32 s1, s15, s1
	s_lshl_b32 s5, s5, 16
	v_readlane_b32 s15, v255, 24
	s_add_i32 s14, s20, s14
	v_readlane_b32 s21, v255, 23
	s_add_i32 s5, s15, s5
	s_ashr_i32 s15, s14, 31
	s_lshl_b64 s[20:21], s[14:15], 10
	s_mul_hi_i32 s15, s14, 0x60
	s_mulk_i32 s14, 0x60
	v_lshl_add_u64 v[8:9], v[0:1], 0, s[20:21]
	v_mov_b32_e32 v11, s15
	v_or_b32_e32 v10, s14, v6
	v_add_u32_e32 v120, 0x500000, v10
	v_add_u32_e32 v121, 0xc00, v120
	global_load_dword v180, v120, s[62:63] offset:0
	global_load_dword v181, v120, s[62:63] offset:32
	global_load_dword v182, v120, s[62:63] offset:64
	global_load_dword v183, v120, s[62:63] offset:768
	global_load_dword v184, v120, s[62:63] offset:800
	global_load_dword v185, v120, s[62:63] offset:832
	global_load_dword v186, v120, s[62:63] offset:1536
	global_load_dword v187, v120, s[62:63] offset:1568
	global_load_dword v188, v120, s[62:63] offset:1600
	global_load_dword v189, v120, s[62:63] offset:2304
	global_load_dword v190, v120, s[62:63] offset:2336
	global_load_dword v191, v120, s[62:63] offset:2368
	global_load_dword v192, v121, s[62:63] offset:0
	global_load_dword v193, v121, s[62:63] offset:32
	global_load_dword v194, v121, s[62:63] offset:64
	global_load_dword v195, v121, s[62:63] offset:768
	global_load_dword v196, v121, s[62:63] offset:800
	global_load_dword v197, v121, s[62:63] offset:832
	global_load_dword v198, v121, s[62:63] offset:1536
	global_load_dword v199, v121, s[62:63] offset:1568
	global_load_dword v200, v121, s[62:63] offset:1600
	global_load_dword v201, v121, s[62:63] offset:2304
	global_load_dword v202, v121, s[62:63] offset:2336
	global_load_dword v203, v121, s[62:63] offset:2368
	s_ashr_i32 s14, s13, 12
	s_mulk_i32 s14, 0x48
	v_or_b32_e32 v122, s14, v2
	v_lshlrev_b32_e32 v122, 19, v122
	v_mov_b32_e32 v123, v1
	v_lshl_add_u64 v[122:123], v[4:5], 0, v[122:123]
	s_and_b32 s15, s13, 0xfff
	s_lshl_b32 s70, s15, 7
	v_lshl_add_u64 v[124:125], v[122:123], 0, s[70:71]
	s_addk_i32 s70, 0x1000
	v_lshl_add_u64 v[126:127], v[122:123], 0, s[70:71]
	s_and_b32 s14, s15, 3
	s_lshl_b32 s14, s14, 10
	s_lshr_b32 s20, s15, 2
	s_or_b32 s14, s14, s20
	s_lshl_b32 s70, s14, 7
	s_add_i32 s70, s70, 0x400000
	v_lshl_add_u64 v[128:129], v[122:123], 0, s[70:71]
	s_and_b32 s14, s15, 15
	s_lshl_b32 s14, s14, 8
	s_lshr_b32 s20, s15, 4
	s_or_b32 s14, s14, s20
	s_lshl_b32 s70, s14, 7
	s_add_i32 s70, s70, 0x800000
	v_lshl_add_u64 v[130:131], v[122:123], 0, s[70:71]
	s_add_i32 s70, s70, 0x40000
	v_lshl_add_u64 v[132:133], v[122:123], 0, s[70:71]
	global_load_dwordx4 v[12:15], v[124:125], off offset:0
	global_load_dwordx4 v[16:19], v[128:129], off offset:0
	global_load_dwordx4 v[20:23], v[130:131], off offset:0
	global_load_dwordx4 v[24:27], v[124:125], off offset:1024
	global_load_dwordx4 v[28:31], v[128:129], off offset:256
	global_load_dwordx4 v[32:35], v[132:133], off offset:0
	global_load_dwordx4 v[36:39], v[124:125], off offset:2048
	global_load_dwordx4 v[40:43], v[128:129], off offset:512
	global_load_dwordx4 v[44:47], v[130:131], off offset:128
	global_load_dwordx4 v[48:51], v[124:125], off offset:3072
	global_load_dwordx4 v[52:55], v[128:129], off offset:768
	global_load_dwordx4 v[56:59], v[132:133], off offset:128
	global_load_dwordx4 v[60:63], v[126:127], off offset:0
	global_load_dwordx4 v[64:67], v[128:129], off offset:1024
	global_load_dwordx4 v[68:71], v[130:131], off offset:256
	global_load_dwordx4 v[72:75], v[126:127], off offset:1024
	global_load_dwordx4 v[76:79], v[128:129], off offset:1280
	global_load_dwordx4 v[80:83], v[132:133], off offset:256
	global_load_dwordx4 v[84:87], v[126:127], off offset:2048
	global_load_dwordx4 v[88:91], v[128:129], off offset:1536
	global_load_dwordx4 v[92:95], v[130:131], off offset:384
	global_load_dwordx4 v[96:99], v[126:127], off offset:3072
	global_load_dwordx4 v[100:103], v[128:129], off offset:1792
	global_load_dwordx4 v[104:107], v[132:133], off offset:384
	v_lshl_add_u64 v[134:135], s[62:63], 0, v[8:9]
	s_mov_b64 s[20:21], 0x2000
	s_waitcnt vmcnt(21)
; __device__ __forceinline__ unsigned cvtpk(float lo, float hi) { f32x2_t v = {lo, hi}; f16x2_t b = __builtin_convertvector(v, f16x2_t); return __builtin_bit_cast(unsigned, b); }
; __device__ __forceinline__ float bflo(unsigned w) { const f16x2_t b = __builtin_bit_cast(f16x2_t, w); return (float)b[0]; }
; __device__ __forceinline__ float bfhi(unsigned w) { const f16x2_t b = __builtin_bit_cast(f16x2_t, w); return (float)b[1]; }
; __device__ __forceinline__ void combine_rows(const Frame& F, int r0, int r1, const bf16* P, const float* LSE, bf16* COMB) {
;     ...
;         const float l0 = LSE[(size_t)row * 24 + h], l1 = LSE[(size_t)row * 24 + 8 + h], l2 = LSE[(size_t)row * 24 + 16 + h];
;         const float mx = fmaxf(l0, fmaxf(l1, l2));
;         float e0 = __builtin_amdgcn_exp2f((l0 - mx) * 1.4426950408889634f), e1 = __builtin_amdgcn_exp2f((l1 - mx) * 1.4426950408889634f), e2 = __builtin_amdgcn_exp2f((l2 - mx) * 1.4426950408889634f);
;         const float inv = 1.0f / (e0 + e1 + e2); e0 *= inv; e1 *= inv; e2 *= inv;
;         const int bl = row >> 12, t = row & 4095, ch = lane & 7;
;         const bf16* hb = P + PL_A + ((size_t)(bl * 3 * 24 + h) * 4096) * 64 + ch * 8;
;         const u32x4 a = *(const u32x4*)(hb + (size_t)t * 64), b = *(const u32x4*)(hb + ((size_t)8 * 4096 + ((t & 3) << 10) + (t >> 2)) * 64), c = *(const u32x4*)(hb + ((size_t)16 * 4096 + ((t & 15) << 8) + (t >> 4)) * 64);
;         u32x4 o;
;         o.x = cvtpk(e0 * bflo(a.x) + e1 * bflo(b.x) + e2 * bflo(c.x), e0 * bfhi(a.x) + e1 * bfhi(b.x) + e2 * bfhi(c.x));
;         o.y = cvtpk(e0 * bflo(a.y) + e1 * bflo(b.y) + e2 * bflo(c.y), e0 * bfhi(a.y) + e1 * bfhi(b.y) + e2 * bfhi(c.y));
;         o.z = cvtpk(e0 * bflo(a.z) + e1 * bflo(b.z) + e2 * bflo(c.z), e0 * bfhi(a.z) + e1 * bfhi(b.z) + e2 * bfhi(c.z));
;         o.w = cvtpk(e0 * bflo(a.w) + e1 * bflo(b.w) + e2 * bflo(c.w), e0 * bfhi(a.w) + e1 * bfhi(b.w) + e2 * bfhi(c.w));
;         *(u32x4*)(COMB + (size_t)row * 512 + lane * 8) = o;
	v_max3_f32 v109, v180, v181, v182
	v_sub_f32_e32 v180, v180, v109
	v_mul_f32_e32 v180, 0x3fb8aa3b, v180
	v_exp_f32_e32 v111, v180
	v_sub_f32_e32 v180, v181, v109
	v_mul_f32_e32 v180, 0x3fb8aa3b, v180
	v_exp_f32_e32 v110, v180
	v_sub_f32_e32 v180, v182, v109
	v_mul_f32_e32 v180, 0x3fb8aa3b, v180
	v_exp_f32_e32 v180, v180
	v_add_f32_e32 v181, v111, v110
	v_add_f32_e32 v181, v180, v181
	v_div_scale_f32 v108, s[14:15], v181, v181, 1.0
	v_rcp_f32_e32 v109, v108
	s_nop 0
	v_fma_f32 v112, -v108, v109, 1.0
	v_fmac_f32_e32 v109, v112, v109
	v_div_scale_f32 v112, vcc, 1.0, v181, 1.0
	v_mul_f32_e32 v113, v112, v109
	v_fma_f32 v118, -v108, v113, v112
	v_fmac_f32_e32 v113, v118, v109
	v_fma_f32 v108, -v108, v113, v112
	s_nop 1
	v_div_fmas_f32 v108, v108, v109, v113
	v_div_fixup_f32 v112, v108, v181, 1.0
	v_mul_f32_e32 v108, v180, v112
	v_pk_mul_f32 v[114:115], v[110:111], v[112:113] op_sel_hi:[1,0]
	v_cvt_f32_f16_e32 v112, v12
	v_cvt_f32_f16_sdwa v111, v12 dst_sel:DWORD dst_unused:UNUSED_PAD src0_sel:WORD_1
	v_cvt_f32_f16_sdwa v113, v16 dst_sel:DWORD dst_unused:UNUSED_PAD src0_sel:WORD_1
	v_cvt_f32_f16_e32 v110, v16
	v_cvt_f32_f16_e32 v16, v13
	v_pk_mul_f32 v[112:113], v[114:115], v[112:113] op_sel:[1,0] op_sel_hi:[0,1]
	v_pk_fma_f32 v[110:111], v[114:115], v[110:111], v[112:113]
	v_cvt_f32_f16_e32 v112, v17
	v_cvt_f32_f16_sdwa v17, v17 dst_sel:DWORD dst_unused:UNUSED_PAD src0_sel:WORD_1
	v_cvt_f32_f16_sdwa v113, v13 dst_sel:DWORD dst_unused:UNUSED_PAD src0_sel:WORD_1
	v_pk_mul_f32 v[16:17], v[114:115], v[16:17] op_sel:[1,0] op_sel_hi:[0,1]
	v_cvt_f32_f16_e32 v116, v20
	v_cvt_f32_f16_sdwa v117, v20 dst_sel:DWORD dst_unused:UNUSED_PAD src0_sel:WORD_1
	v_cvt_f32_f16_e32 v12, v21
	v_cvt_f32_f16_sdwa v13, v21 dst_sel:DWORD dst_unused:UNUSED_PAD src0_sel:WORD_1
	v_pk_fma_f32 v[112:113], v[114:115], v[112:113], v[16:17]
	v_pk_fma_f32 v[110:111], v[108:109], v[116:117], v[110:111] op_sel_hi:[0,1,1]
	v_cvt_pk_f16_f32 v110, v110, v111
	v_pk_fma_f32 v[112:113], v[108:109], v[12:13], v[112:113] op_sel_hi:[0,1,1]
	v_cvt_f32_f16_sdwa v13, v18 dst_sel:DWORD dst_unused:UNUSED_PAD src0_sel:WORD_1
	v_cvt_f32_f16_e32 v12, v14
	v_cvt_pk_f16_f32 v111, v112, v113
	v_cvt_f32_f16_e32 v112, v18
	v_cvt_f32_f16_sdwa v113, v14 dst_sel:DWORD dst_unused:UNUSED_PAD src0_sel:WORD_1
	v_cvt_f32_f16_e32 v16, v22
	v_cvt_f32_f16_sdwa v17, v22 dst_sel:DWORD dst_unused:UNUSED_PAD src0_sel:WORD_1
	v_pk_mul_f32 v[12:13], v[114:115], v[12:13] op_sel:[1,0] op_sel_hi:[0,1]
	v_pk_fma_f32 v[112:113], v[114:115], v[112:113], v[12:13]
	v_cvt_f32_f16_e32 v12, v19
	v_pk_fma_f32 v[112:113], v[108:109], v[16:17], v[112:113] op_sel_hi:[0,1,1]
	v_cvt_f32_f16_sdwa v17, v19 dst_sel:DWORD dst_unused:UNUSED_PAD src0_sel:WORD_1
	v_cvt_f32_f16_e32 v16, v15
	v_cvt_f32_f16_sdwa v13, v15 dst_sel:DWORD dst_unused:UNUSED_PAD src0_sel:WORD_1
	v_cvt_pk_f16_f32 v112, v112, v113
	v_pk_mul_f32 v[14:15], v[114:115], v[16:17] op_sel:[1,0] op_sel_hi:[0,1]
	v_pk_fma_f32 v[12:13], v[114:115], v[12:13], v[14:15]
	v_cvt_f32_f16_e32 v14, v23
	v_cvt_f32_f16_sdwa v15, v23 dst_sel:DWORD dst_unused:UNUSED_PAD src0_sel:WORD_1
	v_pk_fma_f32 v[108:109], v[108:109], v[14:15], v[12:13] op_sel_hi:[0,1,1]
	v_cvt_pk_f16_f32 v113, v108, v109
	global_store_dwordx4 v[134:135], v[110:113], off
	v_lshl_add_u64 v[134:135], v[134:135], 0, s[20:21]
	s_waitcnt vmcnt(19)
	v_max3_f32 v109, v183, v184, v185
	v_sub_f32_e32 v183, v183, v109
	v_mul_f32_e32 v183, 0x3fb8aa3b, v183
	v_exp_f32_e32 v111, v183
	v_sub_f32_e32 v183, v184, v109
	v_mul_f32_e32 v183, 0x3fb8aa3b, v183
	v_exp_f32_e32 v110, v183
	v_sub_f32_e32 v183, v185, v109
	v_mul_f32_e32 v183, 0x3fb8aa3b, v183
	v_exp_f32_e32 v183, v183
	v_add_f32_e32 v184, v111, v110
	v_add_f32_e32 v184, v183, v184
	v_div_scale_f32 v108, s[14:15], v184, v184, 1.0
	v_rcp_f32_e32 v109, v108
	s_nop 0
	v_fma_f32 v112, -v108, v109, 1.0
	v_fmac_f32_e32 v109, v112, v109
	v_div_scale_f32 v112, vcc, 1.0, v184, 1.0
	v_mul_f32_e32 v113, v112, v109
	v_fma_f32 v118, -v108, v113, v112
	v_fmac_f32_e32 v113, v118, v109
	v_fma_f32 v108, -v108, v113, v112
	s_nop 1
	v_div_fmas_f32 v108, v108, v109, v113
	v_div_fixup_f32 v112, v108, v184, 1.0
	v_mul_f32_e32 v108, v183, v112
	v_pk_mul_f32 v[114:115], v[110:111], v[112:113] op_sel_hi:[1,0]
	v_cvt_f32_f16_e32 v112, v24
	v_cvt_f32_f16_sdwa v111, v24 dst_sel:DWORD dst_unused:UNUSED_PAD src0_sel:WORD_1
	v_cvt_f32_f16_sdwa v113, v28 dst_sel:DWORD dst_unused:UNUSED_PAD src0_sel:WORD_1
	v_cvt_f32_f16_e32 v110, v28
	v_cvt_f32_f16_e32 v28, v25
	v_pk_mul_f32 v[112:113], v[114:115], v[112:113] op_sel:[1,0] op_sel_hi:[0,1]
	v_pk_fma_f32 v[110:111], v[114:115], v[110:111], v[112:113]
	v_cvt_f32_f16_e32 v112, v29
	v_cvt_f32_f16_sdwa v29, v29 dst_sel:DWORD dst_unused:UNUSED_PAD src0_sel:WORD_1
	v_cvt_f32_f16_sdwa v113, v25 dst_sel:DWORD dst_unused:UNUSED_PAD src0_sel:WORD_1
	v_pk_mul_f32 v[28:29], v[114:115], v[28:29] op_sel:[1,0] op_sel_hi:[0,1]
	v_cvt_f32_f16_e32 v116, v32
	v_cvt_f32_f16_sdwa v117, v32 dst_sel:DWORD dst_unused:UNUSED_PAD src0_sel:WORD_1
	v_cvt_f32_f16_e32 v24, v33
	v_cvt_f32_f16_sdwa v25, v33 dst_sel:DWORD dst_unused:UNUSED_PAD src0_sel:WORD_1
	v_pk_fma_f32 v[112:113], v[114:115], v[112:113], v[28:29]
	v_pk_fma_f32 v[110:111], v[108:109], v[116:117], v[110:111] op_sel_hi:[0,1,1]
	v_cvt_pk_f16_f32 v110, v110, v111
	v_pk_fma_f32 v[112:113], v[108:109], v[24:25], v[112:113] op_sel_hi:[0,1,1]
	v_cvt_f32_f16_sdwa v25, v30 dst_sel:DWORD dst_unused:UNUSED_PAD src0_sel:WORD_1
	v_cvt_f32_f16_e32 v24, v26
	v_cvt_pk_f16_f32 v111, v112, v113
	v_cvt_f32_f16_e32 v112, v30
	v_cvt_f32_f16_sdwa v113, v26 dst_sel:DWORD dst_unused:UNUSED_PAD src0_sel:WORD_1
	v_cvt_f32_f16_e32 v28, v34
	v_cvt_f32_f16_sdwa v29, v34 dst_sel:DWORD dst_unused:UNUSED_PAD src0_sel:WORD_1
	v_pk_mul_f32 v[24:25], v[114:115], v[24:25] op_sel:[1,0] op_sel_hi:[0,1]
	v_pk_fma_f32 v[112:113], v[114:115], v[112:113], v[24:25]
	v_cvt_f32_f16_e32 v24, v31
	v_pk_fma_f32 v[112:113], v[108:109], v[28:29], v[112:113] op_sel_hi:[0,1,1]
	v_cvt_f32_f16_sdwa v29, v31 dst_sel:DWORD dst_unused:UNUSED_PAD src0_sel:WORD_1
	v_cvt_f32_f16_e32 v28, v27
	v_cvt_f32_f16_sdwa v25, v27 dst_sel:DWORD dst_unused:UNUSED_PAD src0_sel:WORD_1
	v_cvt_pk_f16_f32 v112, v112, v113
	v_pk_mul_f32 v[26:27], v[114:115], v[28:29] op_sel:[1,0] op_sel_hi:[0,1]
	v_pk_fma_f32 v[24:25], v[114:115], v[24:25], v[26:27]
	v_cvt_f32_f16_e32 v26, v35
	v_cvt_f32_f16_sdwa v27, v35 dst_sel:DWORD dst_unused:UNUSED_PAD src0_sel:WORD_1
	v_pk_fma_f32 v[108:109], v[108:109], v[26:27], v[24:25] op_sel_hi:[0,1,1]
	v_cvt_pk_f16_f32 v113, v108, v109
	global_store_dwordx4 v[134:135], v[110:113], off
	v_lshl_add_u64 v[134:135], v[134:135], 0, s[20:21]
	s_waitcnt vmcnt(17)
; __device__ __forceinline__ unsigned cvtpk(float lo, float hi) { f32x2_t v = {lo, hi}; f16x2_t b = __builtin_convertvector(v, f16x2_t); return __builtin_bit_cast(unsigned, b); }
; __device__ __forceinline__ float bflo(unsigned w) { const f16x2_t b = __builtin_bit_cast(f16x2_t, w); return (float)b[0]; }
; __device__ __forceinline__ float bfhi(unsigned w) { const f16x2_t b = __builtin_bit_cast(f16x2_t, w); return (float)b[1]; }
; __device__ __forceinline__ void combine_rows(const Frame& F, int r0, int r1, const bf16* P, const float* LSE, bf16* COMB) {
;     ...
;         const float l0 = LSE[(size_t)row * 24 + h], l1 = LSE[(size_t)row * 24 + 8 + h], l2 = LSE[(size_t)row * 24 + 16 + h];
;         const float mx = fmaxf(l0, fmaxf(l1, l2));
;         float e0 = __builtin_amdgcn_exp2f((l0 - mx) * 1.4426950408889634f), e1 = __builtin_amdgcn_exp2f((l1 - mx) * 1.4426950408889634f), e2 = __builtin_amdgcn_exp2f((l2 - mx) * 1.4426950408889634f);
;         const float inv = 1.0f / (e0 + e1 + e2); e0 *= inv; e1 *= inv; e2 *= inv;
;         const int bl = row >> 12, t = row & 4095, ch = lane & 7;
;         const bf16* hb = P + PL_A + ((size_t)(bl * 3 * 24 + h) * 4096) * 64 + ch * 8;
;         const u32x4 a = *(const u32x4*)(hb + (size_t)t * 64), b = *(const u32x4*)(hb + ((size_t)8 * 4096 + ((t & 3) << 10) + (t >> 2)) * 64), c = *(const u32x4*)(hb + ((size_t)16 * 4096 + ((t & 15) << 8) + (t >> 4)) * 64);
;         u32x4 o;
;         o.x = cvtpk(e0 * bflo(a.x) + e1 * bflo(b.x) + e2 * bflo(c.x), e0 * bfhi(a.x) + e1 * bfhi(b.x) + e2 * bfhi(c.x));
;         o.y = cvtpk(e0 * bflo(a.y) + e1 * bflo(b.y) + e2 * bflo(c.y), e0 * bfhi(a.y) + e1 * bfhi(b.y) + e2 * bfhi(c.y));
;         o.z = cvtpk(e0 * bflo(a.z) + e1 * bflo(b.z) + e2 * bflo(c.z), e0 * bfhi(a.z) + e1 * bfhi(b.z) + e2 * bfhi(c.z));
;         o.w = cvtpk(e0 * bflo(a.w) + e1 * bflo(b.w) + e2 * bflo(c.w), e0 * bfhi(a.w) + e1 * bfhi(b.w) + e2 * bfhi(c.w));
;         *(u32x4*)(COMB + (size_t)row * 512 + lane * 8) = o;
	v_max3_f32 v109, v186, v187, v188
	v_sub_f32_e32 v186, v186, v109
	v_mul_f32_e32 v186, 0x3fb8aa3b, v186
	v_exp_f32_e32 v111, v186
	v_sub_f32_e32 v186, v187, v109
	v_mul_f32_e32 v186, 0x3fb8aa3b, v186
	v_exp_f32_e32 v110, v186
	v_sub_f32_e32 v186, v188, v109
	v_mul_f32_e32 v186, 0x3fb8aa3b, v186
	v_exp_f32_e32 v186, v186
	v_add_f32_e32 v187, v111, v110
	v_add_f32_e32 v187, v186, v187
	v_div_scale_f32 v108, s[14:15], v187, v187, 1.0
	v_rcp_f32_e32 v109, v108
	s_nop 0
	v_fma_f32 v112, -v108, v109, 1.0
	v_fmac_f32_e32 v109, v112, v109
	v_div_scale_f32 v112, vcc, 1.0, v187, 1.0
	v_mul_f32_e32 v113, v112, v109
	v_fma_f32 v118, -v108, v113, v112
	v_fmac_f32_e32 v113, v118, v109
	v_fma_f32 v108, -v108, v113, v112
	s_nop 1
	v_div_fmas_f32 v108, v108, v109, v113
	v_div_fixup_f32 v112, v108, v187, 1.0
	v_mul_f32_e32 v108, v186, v112
	v_pk_mul_f32 v[114:115], v[110:111], v[112:113] op_sel_hi:[1,0]
	v_cvt_f32_f16_e32 v112, v36
	v_cvt_f32_f16_sdwa v111, v36 dst_sel:DWORD dst_unused:UNUSED_PAD src0_sel:WORD_1
	v_cvt_f32_f16_sdwa v113, v40 dst_sel:DWORD dst_unused:UNUSED_PAD src0_sel:WORD_1
	v_cvt_f32_f16_e32 v110, v40
	v_cvt_f32_f16_e32 v40, v37
	v_pk_mul_f32 v[112:113], v[114:115], v[112:113] op_sel:[1,0] op_sel_hi:[0,1]
	v_pk_fma_f32 v[110:111], v[114:115], v[110:111], v[112:113]
	v_cvt_f32_f16_e32 v112, v41
	v_cvt_f32_f16_sdwa v41, v41 dst_sel:DWORD dst_unused:UNUSED_PAD src0_sel:WORD_1
	v_cvt_f32_f16_sdwa v113, v37 dst_sel:DWORD dst_unused:UNUSED_PAD src0_sel:WORD_1
	v_pk_mul_f32 v[40:41], v[114:115], v[40:41] op_sel:[1,0] op_sel_hi:[0,1]
	v_cvt_f32_f16_e32 v116, v44
	v_cvt_f32_f16_sdwa v117, v44 dst_sel:DWORD dst_unused:UNUSED_PAD src0_sel:WORD_1
	v_cvt_f32_f16_e32 v36, v45
	v_cvt_f32_f16_sdwa v37, v45 dst_sel:DWORD dst_unused:UNUSED_PAD src0_sel:WORD_1
	v_pk_fma_f32 v[112:113], v[114:115], v[112:113], v[40:41]
	v_pk_fma_f32 v[110:111], v[108:109], v[116:117], v[110:111] op_sel_hi:[0,1,1]
	v_cvt_pk_f16_f32 v110, v110, v111
	v_pk_fma_f32 v[112:113], v[108:109], v[36:37], v[112:113] op_sel_hi:[0,1,1]
	v_cvt_f32_f16_sdwa v37, v42 dst_sel:DWORD dst_unused:UNUSED_PAD src0_sel:WORD_1
	v_cvt_f32_f16_e32 v36, v38
	v_cvt_pk_f16_f32 v111, v112, v113
	v_cvt_f32_f16_e32 v112, v42
	v_cvt_f32_f16_sdwa v113, v38 dst_sel:DWORD dst_unused:UNUSED_PAD src0_sel:WORD_1
	v_cvt_f32_f16_e32 v40, v46
	v_cvt_f32_f16_sdwa v41, v46 dst_sel:DWORD dst_unused:UNUSED_PAD src0_sel:WORD_1
	v_pk_mul_f32 v[36:37], v[114:115], v[36:37] op_sel:[1,0] op_sel_hi:[0,1]
	v_pk_fma_f32 v[112:113], v[114:115], v[112:113], v[36:37]
	v_cvt_f32_f16_e32 v36, v43
	v_pk_fma_f32 v[112:113], v[108:109], v[40:41], v[112:113] op_sel_hi:[0,1,1]
	v_cvt_f32_f16_sdwa v41, v43 dst_sel:DWORD dst_unused:UNUSED_PAD src0_sel:WORD_1
	v_cvt_f32_f16_e32 v40, v39
	v_cvt_f32_f16_sdwa v37, v39 dst_sel:DWORD dst_unused:UNUSED_PAD src0_sel:WORD_1
	v_cvt_pk_f16_f32 v112, v112, v113
	v_pk_mul_f32 v[38:39], v[114:115], v[40:41] op_sel:[1,0] op_sel_hi:[0,1]
	v_pk_fma_f32 v[36:37], v[114:115], v[36:37], v[38:39]
	v_cvt_f32_f16_e32 v38, v47
	v_cvt_f32_f16_sdwa v39, v47 dst_sel:DWORD dst_unused:UNUSED_PAD src0_sel:WORD_1
	v_pk_fma_f32 v[108:109], v[108:109], v[38:39], v[36:37] op_sel_hi:[0,1,1]
	v_cvt_pk_f16_f32 v113, v108, v109
	global_store_dwordx4 v[134:135], v[110:113], off
	v_lshl_add_u64 v[134:135], v[134:135], 0, s[20:21]
	s_waitcnt vmcnt(15)
	v_max3_f32 v109, v189, v190, v191
	v_sub_f32_e32 v189, v189, v109
	v_mul_f32_e32 v189, 0x3fb8aa3b, v189
	v_exp_f32_e32 v111, v189
	v_sub_f32_e32 v189, v190, v109
	v_mul_f32_e32 v189, 0x3fb8aa3b, v189
	v_exp_f32_e32 v110, v189
	v_sub_f32_e32 v189, v191, v109
	v_mul_f32_e32 v189, 0x3fb8aa3b, v189
	v_exp_f32_e32 v189, v189
	v_add_f32_e32 v190, v111, v110
	v_add_f32_e32 v190, v189, v190
	v_div_scale_f32 v108, s[14:15], v190, v190, 1.0
	v_rcp_f32_e32 v109, v108
	s_nop 0
	v_fma_f32 v112, -v108, v109, 1.0
	v_fmac_f32_e32 v109, v112, v109
	v_div_scale_f32 v112, vcc, 1.0, v190, 1.0
	v_mul_f32_e32 v113, v112, v109
	v_fma_f32 v118, -v108, v113, v112
	v_fmac_f32_e32 v113, v118, v109
	v_fma_f32 v108, -v108, v113, v112
	s_nop 1
	v_div_fmas_f32 v108, v108, v109, v113
	v_div_fixup_f32 v112, v108, v190, 1.0
	v_mul_f32_e32 v108, v189, v112
	v_pk_mul_f32 v[114:115], v[110:111], v[112:113] op_sel_hi:[1,0]
	v_cvt_f32_f16_e32 v112, v48
	v_cvt_f32_f16_sdwa v111, v48 dst_sel:DWORD dst_unused:UNUSED_PAD src0_sel:WORD_1
	v_cvt_f32_f16_sdwa v113, v52 dst_sel:DWORD dst_unused:UNUSED_PAD src0_sel:WORD_1
	v_cvt_f32_f16_e32 v110, v52
	v_cvt_f32_f16_e32 v52, v49
	v_pk_mul_f32 v[112:113], v[114:115], v[112:113] op_sel:[1,0] op_sel_hi:[0,1]
	v_pk_fma_f32 v[110:111], v[114:115], v[110:111], v[112:113]
	v_cvt_f32_f16_e32 v112, v53
	v_cvt_f32_f16_sdwa v53, v53 dst_sel:DWORD dst_unused:UNUSED_PAD src0_sel:WORD_1
	v_cvt_f32_f16_sdwa v113, v49 dst_sel:DWORD dst_unused:UNUSED_PAD src0_sel:WORD_1
	v_pk_mul_f32 v[52:53], v[114:115], v[52:53] op_sel:[1,0] op_sel_hi:[0,1]
	v_cvt_f32_f16_e32 v116, v56
	v_cvt_f32_f16_sdwa v117, v56 dst_sel:DWORD dst_unused:UNUSED_PAD src0_sel:WORD_1
	v_cvt_f32_f16_e32 v48, v57
	v_cvt_f32_f16_sdwa v49, v57 dst_sel:DWORD dst_unused:UNUSED_PAD src0_sel:WORD_1
	v_pk_fma_f32 v[112:113], v[114:115], v[112:113], v[52:53]
	v_pk_fma_f32 v[110:111], v[108:109], v[116:117], v[110:111] op_sel_hi:[0,1,1]
	v_cvt_pk_f16_f32 v110, v110, v111
	v_pk_fma_f32 v[112:113], v[108:109], v[48:49], v[112:113] op_sel_hi:[0,1,1]
	v_cvt_f32_f16_sdwa v49, v54 dst_sel:DWORD dst_unused:UNUSED_PAD src0_sel:WORD_1
	v_cvt_f32_f16_e32 v48, v50
	v_cvt_pk_f16_f32 v111, v112, v113
	v_cvt_f32_f16_e32 v112, v54
	v_cvt_f32_f16_sdwa v113, v50 dst_sel:DWORD dst_unused:UNUSED_PAD src0_sel:WORD_1
	v_cvt_f32_f16_e32 v52, v58
	v_cvt_f32_f16_sdwa v53, v58 dst_sel:DWORD dst_unused:UNUSED_PAD src0_sel:WORD_1
	v_pk_mul_f32 v[48:49], v[114:115], v[48:49] op_sel:[1,0] op_sel_hi:[0,1]
	v_pk_fma_f32 v[112:113], v[114:115], v[112:113], v[48:49]
	v_cvt_f32_f16_e32 v48, v55
	v_pk_fma_f32 v[112:113], v[108:109], v[52:53], v[112:113] op_sel_hi:[0,1,1]
	v_cvt_f32_f16_sdwa v53, v55 dst_sel:DWORD dst_unused:UNUSED_PAD src0_sel:WORD_1
	v_cvt_f32_f16_e32 v52, v51
	v_cvt_f32_f16_sdwa v49, v51 dst_sel:DWORD dst_unused:UNUSED_PAD src0_sel:WORD_1
	v_cvt_pk_f16_f32 v112, v112, v113
	v_pk_mul_f32 v[50:51], v[114:115], v[52:53] op_sel:[1,0] op_sel_hi:[0,1]
	v_pk_fma_f32 v[48:49], v[114:115], v[48:49], v[50:51]
	v_cvt_f32_f16_e32 v50, v59
	v_cvt_f32_f16_sdwa v51, v59 dst_sel:DWORD dst_unused:UNUSED_PAD src0_sel:WORD_1
	v_pk_fma_f32 v[108:109], v[108:109], v[50:51], v[48:49] op_sel_hi:[0,1,1]
	v_cvt_pk_f16_f32 v113, v108, v109
	global_store_dwordx4 v[134:135], v[110:113], off
	v_lshl_add_u64 v[134:135], v[134:135], 0, s[20:21]
	s_waitcnt vmcnt(13)
; __device__ __forceinline__ unsigned cvtpk(float lo, float hi) { f32x2_t v = {lo, hi}; f16x2_t b = __builtin_convertvector(v, f16x2_t); return __builtin_bit_cast(unsigned, b); }
; __device__ __forceinline__ float bflo(unsigned w) { const f16x2_t b = __builtin_bit_cast(f16x2_t, w); return (float)b[0]; }
; __device__ __forceinline__ float bfhi(unsigned w) { const f16x2_t b = __builtin_bit_cast(f16x2_t, w); return (float)b[1]; }
; __device__ __forceinline__ void combine_rows(const Frame& F, int r0, int r1, const bf16* P, const float* LSE, bf16* COMB) {
;     ...
;         const float l0 = LSE[(size_t)row * 24 + h], l1 = LSE[(size_t)row * 24 + 8 + h], l2 = LSE[(size_t)row * 24 + 16 + h];
;         const float mx = fmaxf(l0, fmaxf(l1, l2));
;         float e0 = __builtin_amdgcn_exp2f((l0 - mx) * 1.4426950408889634f), e1 = __builtin_amdgcn_exp2f((l1 - mx) * 1.4426950408889634f), e2 = __builtin_amdgcn_exp2f((l2 - mx) * 1.4426950408889634f);
;         const float inv = 1.0f / (e0 + e1 + e2); e0 *= inv; e1 *= inv; e2 *= inv;
;         const int bl = row >> 12, t = row & 4095, ch = lane & 7;
;         const bf16* hb = P + PL_A + ((size_t)(bl * 3 * 24 + h) * 4096) * 64 + ch * 8;
;         const u32x4 a = *(const u32x4*)(hb + (size_t)t * 64), b = *(const u32x4*)(hb + ((size_t)8 * 4096 + ((t & 3) << 10) + (t >> 2)) * 64), c = *(const u32x4*)(hb + ((size_t)16 * 4096 + ((t & 15) << 8) + (t >> 4)) * 64);
;         u32x4 o;
;         o.x = cvtpk(e0 * bflo(a.x) + e1 * bflo(b.x) + e2 * bflo(c.x), e0 * bfhi(a.x) + e1 * bfhi(b.x) + e2 * bfhi(c.x));
;         o.y = cvtpk(e0 * bflo(a.y) + e1 * bflo(b.y) + e2 * bflo(c.y), e0 * bfhi(a.y) + e1 * bfhi(b.y) + e2 * bfhi(c.y));
;         o.z = cvtpk(e0 * bflo(a.z) + e1 * bflo(b.z) + e2 * bflo(c.z), e0 * bfhi(a.z) + e1 * bfhi(b.z) + e2 * bfhi(c.z));
;         o.w = cvtpk(e0 * bflo(a.w) + e1 * bflo(b.w) + e2 * bflo(c.w), e0 * bfhi(a.w) + e1 * bfhi(b.w) + e2 * bfhi(c.w));
;         *(u32x4*)(COMB + (size_t)row * 512 + lane * 8) = o;
	v_max3_f32 v109, v192, v193, v194
	v_sub_f32_e32 v192, v192, v109
	v_mul_f32_e32 v192, 0x3fb8aa3b, v192
	v_exp_f32_e32 v111, v192
	v_sub_f32_e32 v192, v193, v109
	v_mul_f32_e32 v192, 0x3fb8aa3b, v192
	v_exp_f32_e32 v110, v192
	v_sub_f32_e32 v192, v194, v109
	v_mul_f32_e32 v192, 0x3fb8aa3b, v192
	v_exp_f32_e32 v192, v192
	v_add_f32_e32 v193, v111, v110
	v_add_f32_e32 v193, v192, v193
	v_div_scale_f32 v108, s[14:15], v193, v193, 1.0
	v_rcp_f32_e32 v109, v108
	s_nop 0
	v_fma_f32 v112, -v108, v109, 1.0
	v_fmac_f32_e32 v109, v112, v109
	v_div_scale_f32 v112, vcc, 1.0, v193, 1.0
	v_mul_f32_e32 v113, v112, v109
	v_fma_f32 v118, -v108, v113, v112
	v_fmac_f32_e32 v113, v118, v109
	v_fma_f32 v108, -v108, v113, v112
	s_nop 1
	v_div_fmas_f32 v108, v108, v109, v113
	v_div_fixup_f32 v112, v108, v193, 1.0
	v_mul_f32_e32 v108, v192, v112
	v_pk_mul_f32 v[114:115], v[110:111], v[112:113] op_sel_hi:[1,0]
	v_cvt_f32_f16_e32 v112, v60
	v_cvt_f32_f16_sdwa v111, v60 dst_sel:DWORD dst_unused:UNUSED_PAD src0_sel:WORD_1
	v_cvt_f32_f16_sdwa v113, v64 dst_sel:DWORD dst_unused:UNUSED_PAD src0_sel:WORD_1
	v_cvt_f32_f16_e32 v110, v64
	v_cvt_f32_f16_e32 v64, v61
	v_pk_mul_f32 v[112:113], v[114:115], v[112:113] op_sel:[1,0] op_sel_hi:[0,1]
	v_pk_fma_f32 v[110:111], v[114:115], v[110:111], v[112:113]
	v_cvt_f32_f16_e32 v112, v65
	v_cvt_f32_f16_sdwa v65, v65 dst_sel:DWORD dst_unused:UNUSED_PAD src0_sel:WORD_1
	v_cvt_f32_f16_sdwa v113, v61 dst_sel:DWORD dst_unused:UNUSED_PAD src0_sel:WORD_1
	v_pk_mul_f32 v[64:65], v[114:115], v[64:65] op_sel:[1,0] op_sel_hi:[0,1]
	v_cvt_f32_f16_e32 v116, v68
	v_cvt_f32_f16_sdwa v117, v68 dst_sel:DWORD dst_unused:UNUSED_PAD src0_sel:WORD_1
	v_cvt_f32_f16_e32 v60, v69
	v_cvt_f32_f16_sdwa v61, v69 dst_sel:DWORD dst_unused:UNUSED_PAD src0_sel:WORD_1
	v_pk_fma_f32 v[112:113], v[114:115], v[112:113], v[64:65]
	v_pk_fma_f32 v[110:111], v[108:109], v[116:117], v[110:111] op_sel_hi:[0,1,1]
	v_cvt_pk_f16_f32 v110, v110, v111
	v_pk_fma_f32 v[112:113], v[108:109], v[60:61], v[112:113] op_sel_hi:[0,1,1]
	v_cvt_f32_f16_sdwa v61, v66 dst_sel:DWORD dst_unused:UNUSED_PAD src0_sel:WORD_1
	v_cvt_f32_f16_e32 v60, v62
	v_cvt_pk_f16_f32 v111, v112, v113
	v_cvt_f32_f16_e32 v112, v66
	v_cvt_f32_f16_sdwa v113, v62 dst_sel:DWORD dst_unused:UNUSED_PAD src0_sel:WORD_1
	v_cvt_f32_f16_e32 v64, v70
	v_cvt_f32_f16_sdwa v65, v70 dst_sel:DWORD dst_unused:UNUSED_PAD src0_sel:WORD_1
	v_pk_mul_f32 v[60:61], v[114:115], v[60:61] op_sel:[1,0] op_sel_hi:[0,1]
	v_pk_fma_f32 v[112:113], v[114:115], v[112:113], v[60:61]
	v_cvt_f32_f16_e32 v60, v67
	v_pk_fma_f32 v[112:113], v[108:109], v[64:65], v[112:113] op_sel_hi:[0,1,1]
	v_cvt_f32_f16_sdwa v65, v67 dst_sel:DWORD dst_unused:UNUSED_PAD src0_sel:WORD_1
	v_cvt_f32_f16_e32 v64, v63
	v_cvt_f32_f16_sdwa v61, v63 dst_sel:DWORD dst_unused:UNUSED_PAD src0_sel:WORD_1
	v_cvt_pk_f16_f32 v112, v112, v113
	v_pk_mul_f32 v[62:63], v[114:115], v[64:65] op_sel:[1,0] op_sel_hi:[0,1]
	v_pk_fma_f32 v[60:61], v[114:115], v[60:61], v[62:63]
	v_cvt_f32_f16_e32 v62, v71
	v_cvt_f32_f16_sdwa v63, v71 dst_sel:DWORD dst_unused:UNUSED_PAD src0_sel:WORD_1
	v_pk_fma_f32 v[108:109], v[108:109], v[62:63], v[60:61] op_sel_hi:[0,1,1]
	v_cvt_pk_f16_f32 v113, v108, v109
	global_store_dwordx4 v[134:135], v[110:113], off
	v_lshl_add_u64 v[134:135], v[134:135], 0, s[20:21]
	s_waitcnt vmcnt(11)
	v_max3_f32 v109, v195, v196, v197
	v_sub_f32_e32 v195, v195, v109
	v_mul_f32_e32 v195, 0x3fb8aa3b, v195
	v_exp_f32_e32 v111, v195
	v_sub_f32_e32 v195, v196, v109
	v_mul_f32_e32 v195, 0x3fb8aa3b, v195
	v_exp_f32_e32 v110, v195
	v_sub_f32_e32 v195, v197, v109
	v_mul_f32_e32 v195, 0x3fb8aa3b, v195
	v_exp_f32_e32 v195, v195
	v_add_f32_e32 v196, v111, v110
	v_add_f32_e32 v196, v195, v196
	v_div_scale_f32 v108, s[14:15], v196, v196, 1.0
	v_rcp_f32_e32 v109, v108
	s_nop 0
	v_fma_f32 v112, -v108, v109, 1.0
	v_fmac_f32_e32 v109, v112, v109
	v_div_scale_f32 v112, vcc, 1.0, v196, 1.0
	v_mul_f32_e32 v113, v112, v109
	v_fma_f32 v118, -v108, v113, v112
	v_fmac_f32_e32 v113, v118, v109
	v_fma_f32 v108, -v108, v113, v112
	s_nop 1
	v_div_fmas_f32 v108, v108, v109, v113
	v_div_fixup_f32 v112, v108, v196, 1.0
	v_mul_f32_e32 v108, v195, v112
	v_pk_mul_f32 v[114:115], v[110:111], v[112:113] op_sel_hi:[1,0]
	v_cvt_f32_f16_e32 v112, v72
	v_cvt_f32_f16_sdwa v111, v72 dst_sel:DWORD dst_unused:UNUSED_PAD src0_sel:WORD_1
	v_cvt_f32_f16_sdwa v113, v76 dst_sel:DWORD dst_unused:UNUSED_PAD src0_sel:WORD_1
	v_cvt_f32_f16_e32 v110, v76
	v_cvt_f32_f16_e32 v76, v73
	v_pk_mul_f32 v[112:113], v[114:115], v[112:113] op_sel:[1,0] op_sel_hi:[0,1]
	v_pk_fma_f32 v[110:111], v[114:115], v[110:111], v[112:113]
	v_cvt_f32_f16_e32 v112, v77
	v_cvt_f32_f16_sdwa v77, v77 dst_sel:DWORD dst_unused:UNUSED_PAD src0_sel:WORD_1
	v_cvt_f32_f16_sdwa v113, v73 dst_sel:DWORD dst_unused:UNUSED_PAD src0_sel:WORD_1
	v_pk_mul_f32 v[76:77], v[114:115], v[76:77] op_sel:[1,0] op_sel_hi:[0,1]
	v_cvt_f32_f16_e32 v116, v80
	v_cvt_f32_f16_sdwa v117, v80 dst_sel:DWORD dst_unused:UNUSED_PAD src0_sel:WORD_1
	v_cvt_f32_f16_e32 v72, v81
	v_cvt_f32_f16_sdwa v73, v81 dst_sel:DWORD dst_unused:UNUSED_PAD src0_sel:WORD_1
	v_pk_fma_f32 v[112:113], v[114:115], v[112:113], v[76:77]
	v_pk_fma_f32 v[110:111], v[108:109], v[116:117], v[110:111] op_sel_hi:[0,1,1]
	v_cvt_pk_f16_f32 v110, v110, v111
	v_pk_fma_f32 v[112:113], v[108:109], v[72:73], v[112:113] op_sel_hi:[0,1,1]
	v_cvt_f32_f16_sdwa v73, v78 dst_sel:DWORD dst_unused:UNUSED_PAD src0_sel:WORD_1
	v_cvt_f32_f16_e32 v72, v74
	v_cvt_pk_f16_f32 v111, v112, v113
	v_cvt_f32_f16_e32 v112, v78
	v_cvt_f32_f16_sdwa v113, v74 dst_sel:DWORD dst_unused:UNUSED_PAD src0_sel:WORD_1
	v_cvt_f32_f16_e32 v76, v82
	v_cvt_f32_f16_sdwa v77, v82 dst_sel:DWORD dst_unused:UNUSED_PAD src0_sel:WORD_1
	v_pk_mul_f32 v[72:73], v[114:115], v[72:73] op_sel:[1,0] op_sel_hi:[0,1]
	v_pk_fma_f32 v[112:113], v[114:115], v[112:113], v[72:73]
	v_cvt_f32_f16_e32 v72, v79
	v_pk_fma_f32 v[112:113], v[108:109], v[76:77], v[112:113] op_sel_hi:[0,1,1]
	v_cvt_f32_f16_sdwa v77, v79 dst_sel:DWORD dst_unused:UNUSED_PAD src0_sel:WORD_1
	v_cvt_f32_f16_e32 v76, v75
	v_cvt_f32_f16_sdwa v73, v75 dst_sel:DWORD dst_unused:UNUSED_PAD src0_sel:WORD_1
	v_cvt_pk_f16_f32 v112, v112, v113
	v_pk_mul_f32 v[74:75], v[114:115], v[76:77] op_sel:[1,0] op_sel_hi:[0,1]
	v_pk_fma_f32 v[72:73], v[114:115], v[72:73], v[74:75]
	v_cvt_f32_f16_e32 v74, v83
	v_cvt_f32_f16_sdwa v75, v83 dst_sel:DWORD dst_unused:UNUSED_PAD src0_sel:WORD_1
	v_pk_fma_f32 v[108:109], v[108:109], v[74:75], v[72:73] op_sel_hi:[0,1,1]
	v_cvt_pk_f16_f32 v113, v108, v109
	global_store_dwordx4 v[134:135], v[110:113], off
	v_lshl_add_u64 v[134:135], v[134:135], 0, s[20:21]
	s_waitcnt vmcnt(9)
; __device__ __forceinline__ unsigned cvtpk(float lo, float hi) { f32x2_t v = {lo, hi}; f16x2_t b = __builtin_convertvector(v, f16x2_t); return __builtin_bit_cast(unsigned, b); }
; __device__ __forceinline__ float bflo(unsigned w) { const f16x2_t b = __builtin_bit_cast(f16x2_t, w); return (float)b[0]; }
; __device__ __forceinline__ float bfhi(unsigned w) { const f16x2_t b = __builtin_bit_cast(f16x2_t, w); return (float)b[1]; }
; __device__ __forceinline__ void combine_rows(const Frame& F, int r0, int r1, const bf16* P, const float* LSE, bf16* COMB) {
;     const int lane = F.lane, h = lane >> 3;
;     for (int row = r0 + F.wave; row < r1; row += NWAVES) {
;         const float l0 = LSE[(size_t)row * 24 + h], l1 = LSE[(size_t)row * 24 + 8 + h], l2 = LSE[(size_t)row * 24 + 16 + h];
;         const float mx = fmaxf(l0, fmaxf(l1, l2));
;         float e0 = __builtin_amdgcn_exp2f((l0 - mx) * 1.4426950408889634f), e1 = __builtin_amdgcn_exp2f((l1 - mx) * 1.4426950408889634f), e2 = __builtin_amdgcn_exp2f((l2 - mx) * 1.4426950408889634f);
;         const float inv = 1.0f / (e0 + e1 + e2); e0 *= inv; e1 *= inv; e2 *= inv;
;         const int bl = row >> 12, t = row & 4095, ch = lane & 7;
;         const bf16* hb = P + PL_A + ((size_t)(bl * 3 * 24 + h) * 4096) * 64 + ch * 8;
;         const u32x4 a = *(const u32x4*)(hb + (size_t)t * 64), b = *(const u32x4*)(hb + ((size_t)8 * 4096 + ((t & 3) << 10) + (t >> 2)) * 64), c = *(const u32x4*)(hb + ((size_t)16 * 4096 + ((t & 15) << 8) + (t >> 4)) * 64);
;         u32x4 o;
;         o.x = cvtpk(e0 * bflo(a.x) + e1 * bflo(b.x) + e2 * bflo(c.x), e0 * bfhi(a.x) + e1 * bfhi(b.x) + e2 * bfhi(c.x));
;         o.y = cvtpk(e0 * bflo(a.y) + e1 * bflo(b.y) + e2 * bflo(c.y), e0 * bfhi(a.y) + e1 * bfhi(b.y) + e2 * bfhi(c.y));
;         o.z = cvtpk(e0 * bflo(a.z) + e1 * bflo(b.z) + e2 * bflo(c.z), e0 * bfhi(a.z) + e1 * bfhi(b.z) + e2 * bfhi(c.z));
;         o.w = cvtpk(e0 * bflo(a.w) + e1 * bflo(b.w) + e2 * bflo(c.w), e0 * bfhi(a.w) + e1 * bfhi(b.w) + e2 * bfhi(c.w));
;         *(u32x4*)(COMB + (size_t)row * 512 + lane * 8) = o;
;     }
	v_max3_f32 v109, v198, v199, v200
	v_sub_f32_e32 v198, v198, v109
	v_mul_f32_e32 v198, 0x3fb8aa3b, v198
	v_exp_f32_e32 v111, v198
	v_sub_f32_e32 v198, v199, v109
	v_mul_f32_e32 v198, 0x3fb8aa3b, v198
	v_exp_f32_e32 v110, v198
	v_sub_f32_e32 v198, v200, v109
	v_mul_f32_e32 v198, 0x3fb8aa3b, v198
	v_exp_f32_e32 v198, v198
	v_add_f32_e32 v199, v111, v110
	v_add_f32_e32 v199, v198, v199
	v_div_scale_f32 v108, s[14:15], v199, v199, 1.0
	v_rcp_f32_e32 v109, v108
	s_nop 0
	v_fma_f32 v112, -v108, v109, 1.0
	v_fmac_f32_e32 v109, v112, v109
	v_div_scale_f32 v112, vcc, 1.0, v199, 1.0
	v_mul_f32_e32 v113, v112, v109
	v_fma_f32 v118, -v108, v113, v112
	v_fmac_f32_e32 v113, v118, v109
	v_fma_f32 v108, -v108, v113, v112
	s_nop 1
	v_div_fmas_f32 v108, v108, v109, v113
	v_div_fixup_f32 v112, v108, v199, 1.0
	v_mul_f32_e32 v108, v198, v112
	v_pk_mul_f32 v[114:115], v[110:111], v[112:113] op_sel_hi:[1,0]
	v_cvt_f32_f16_e32 v112, v84
	v_cvt_f32_f16_sdwa v111, v84 dst_sel:DWORD dst_unused:UNUSED_PAD src0_sel:WORD_1
	v_cvt_f32_f16_sdwa v113, v88 dst_sel:DWORD dst_unused:UNUSED_PAD src0_sel:WORD_1
	v_cvt_f32_f16_e32 v110, v88
	v_cvt_f32_f16_e32 v88, v85
	v_pk_mul_f32 v[112:113], v[114:115], v[112:113] op_sel:[1,0] op_sel_hi:[0,1]
	v_pk_fma_f32 v[110:111], v[114:115], v[110:111], v[112:113]
	v_cvt_f32_f16_e32 v112, v89
	v_cvt_f32_f16_sdwa v89, v89 dst_sel:DWORD dst_unused:UNUSED_PAD src0_sel:WORD_1
	v_cvt_f32_f16_sdwa v113, v85 dst_sel:DWORD dst_unused:UNUSED_PAD src0_sel:WORD_1
	v_pk_mul_f32 v[88:89], v[114:115], v[88:89] op_sel:[1,0] op_sel_hi:[0,1]
	v_cvt_f32_f16_e32 v116, v92
	v_cvt_f32_f16_sdwa v117, v92 dst_sel:DWORD dst_unused:UNUSED_PAD src0_sel:WORD_1
	v_cvt_f32_f16_e32 v84, v93
	v_cvt_f32_f16_sdwa v85, v93 dst_sel:DWORD dst_unused:UNUSED_PAD src0_sel:WORD_1
	v_pk_fma_f32 v[112:113], v[114:115], v[112:113], v[88:89]
	v_pk_fma_f32 v[110:111], v[108:109], v[116:117], v[110:111] op_sel_hi:[0,1,1]
	v_cvt_pk_f16_f32 v110, v110, v111
	v_pk_fma_f32 v[112:113], v[108:109], v[84:85], v[112:113] op_sel_hi:[0,1,1]
	v_cvt_f32_f16_sdwa v85, v90 dst_sel:DWORD dst_unused:UNUSED_PAD src0_sel:WORD_1
	v_cvt_f32_f16_e32 v84, v86
	v_cvt_pk_f16_f32 v111, v112, v113
	v_cvt_f32_f16_e32 v112, v90
	v_cvt_f32_f16_sdwa v113, v86 dst_sel:DWORD dst_unused:UNUSED_PAD src0_sel:WORD_1
	v_cvt_f32_f16_e32 v88, v94
	v_cvt_f32_f16_sdwa v89, v94 dst_sel:DWORD dst_unused:UNUSED_PAD src0_sel:WORD_1
	v_pk_mul_f32 v[84:85], v[114:115], v[84:85] op_sel:[1,0] op_sel_hi:[0,1]
	v_pk_fma_f32 v[112:113], v[114:115], v[112:113], v[84:85]
	v_cvt_f32_f16_e32 v84, v91
	v_pk_fma_f32 v[112:113], v[108:109], v[88:89], v[112:113] op_sel_hi:[0,1,1]
	v_cvt_f32_f16_sdwa v89, v91 dst_sel:DWORD dst_unused:UNUSED_PAD src0_sel:WORD_1
	v_cvt_f32_f16_e32 v88, v87
	v_cvt_f32_f16_sdwa v85, v87 dst_sel:DWORD dst_unused:UNUSED_PAD src0_sel:WORD_1
	v_cvt_pk_f16_f32 v112, v112, v113
	v_pk_mul_f32 v[86:87], v[114:115], v[88:89] op_sel:[1,0] op_sel_hi:[0,1]
	v_pk_fma_f32 v[84:85], v[114:115], v[84:85], v[86:87]
	v_cvt_f32_f16_e32 v86, v95
	v_cvt_f32_f16_sdwa v87, v95 dst_sel:DWORD dst_unused:UNUSED_PAD src0_sel:WORD_1
	v_pk_fma_f32 v[108:109], v[108:109], v[86:87], v[84:85] op_sel_hi:[0,1,1]
	v_cvt_pk_f16_f32 v113, v108, v109
	global_store_dwordx4 v[134:135], v[110:113], off
	v_lshl_add_u64 v[134:135], v[134:135], 0, s[20:21]
	s_waitcnt vmcnt(7)
	v_max3_f32 v109, v201, v202, v203
	v_sub_f32_e32 v201, v201, v109
	v_mul_f32_e32 v201, 0x3fb8aa3b, v201
	v_exp_f32_e32 v111, v201
	v_sub_f32_e32 v201, v202, v109
	v_mul_f32_e32 v201, 0x3fb8aa3b, v201
	v_exp_f32_e32 v110, v201
	v_sub_f32_e32 v201, v203, v109
	v_mul_f32_e32 v201, 0x3fb8aa3b, v201
	v_exp_f32_e32 v201, v201
	v_add_f32_e32 v202, v111, v110
	v_add_f32_e32 v202, v201, v202
	v_div_scale_f32 v108, s[14:15], v202, v202, 1.0
	v_rcp_f32_e32 v109, v108
	s_nop 0
	v_fma_f32 v112, -v108, v109, 1.0
	v_fmac_f32_e32 v109, v112, v109
	v_div_scale_f32 v112, vcc, 1.0, v202, 1.0
	v_mul_f32_e32 v113, v112, v109
	v_fma_f32 v118, -v108, v113, v112
	v_fmac_f32_e32 v113, v118, v109
	v_fma_f32 v108, -v108, v113, v112
	s_nop 1
	v_div_fmas_f32 v108, v108, v109, v113
	v_div_fixup_f32 v112, v108, v202, 1.0
	v_mul_f32_e32 v108, v201, v112
	v_pk_mul_f32 v[114:115], v[110:111], v[112:113] op_sel_hi:[1,0]
	v_cvt_f32_f16_e32 v112, v96
	v_cvt_f32_f16_sdwa v111, v96 dst_sel:DWORD dst_unused:UNUSED_PAD src0_sel:WORD_1
	v_cvt_f32_f16_sdwa v113, v100 dst_sel:DWORD dst_unused:UNUSED_PAD src0_sel:WORD_1
	v_cvt_f32_f16_e32 v110, v100
	v_cvt_f32_f16_e32 v100, v97
	v_pk_mul_f32 v[112:113], v[114:115], v[112:113] op_sel:[1,0] op_sel_hi:[0,1]
	v_pk_fma_f32 v[110:111], v[114:115], v[110:111], v[112:113]
	v_cvt_f32_f16_e32 v112, v101
	v_cvt_f32_f16_sdwa v101, v101 dst_sel:DWORD dst_unused:UNUSED_PAD src0_sel:WORD_1
	v_cvt_f32_f16_sdwa v113, v97 dst_sel:DWORD dst_unused:UNUSED_PAD src0_sel:WORD_1
	v_pk_mul_f32 v[100:101], v[114:115], v[100:101] op_sel:[1,0] op_sel_hi:[0,1]
	v_cvt_f32_f16_e32 v116, v104
	v_cvt_f32_f16_sdwa v117, v104 dst_sel:DWORD dst_unused:UNUSED_PAD src0_sel:WORD_1
	v_cvt_f32_f16_e32 v96, v105
	v_cvt_f32_f16_sdwa v97, v105 dst_sel:DWORD dst_unused:UNUSED_PAD src0_sel:WORD_1
	v_pk_fma_f32 v[112:113], v[114:115], v[112:113], v[100:101]
	v_pk_fma_f32 v[110:111], v[108:109], v[116:117], v[110:111] op_sel_hi:[0,1,1]
	v_cvt_pk_f16_f32 v110, v110, v111
	v_pk_fma_f32 v[112:113], v[108:109], v[96:97], v[112:113] op_sel_hi:[0,1,1]
	v_cvt_f32_f16_sdwa v97, v102 dst_sel:DWORD dst_unused:UNUSED_PAD src0_sel:WORD_1
	v_cvt_f32_f16_e32 v96, v98
	v_cvt_pk_f16_f32 v111, v112, v113
	v_cvt_f32_f16_e32 v112, v102
	v_cvt_f32_f16_sdwa v113, v98 dst_sel:DWORD dst_unused:UNUSED_PAD src0_sel:WORD_1
	v_cvt_f32_f16_e32 v100, v106
	v_cvt_f32_f16_sdwa v101, v106 dst_sel:DWORD dst_unused:UNUSED_PAD src0_sel:WORD_1
	v_pk_mul_f32 v[96:97], v[114:115], v[96:97] op_sel:[1,0] op_sel_hi:[0,1]
	v_pk_fma_f32 v[112:113], v[114:115], v[112:113], v[96:97]
	v_cvt_f32_f16_e32 v96, v103
	v_pk_fma_f32 v[112:113], v[108:109], v[100:101], v[112:113] op_sel_hi:[0,1,1]
	v_cvt_f32_f16_sdwa v101, v103 dst_sel:DWORD dst_unused:UNUSED_PAD src0_sel:WORD_1
	v_cvt_f32_f16_e32 v100, v99
	v_cvt_f32_f16_sdwa v97, v99 dst_sel:DWORD dst_unused:UNUSED_PAD src0_sel:WORD_1
	v_cvt_pk_f16_f32 v112, v112, v113
	v_pk_mul_f32 v[98:99], v[114:115], v[100:101] op_sel:[1,0] op_sel_hi:[0,1]
	v_pk_fma_f32 v[96:97], v[114:115], v[96:97], v[98:99]
	v_cvt_f32_f16_e32 v98, v107
	v_cvt_f32_f16_sdwa v99, v107 dst_sel:DWORD dst_unused:UNUSED_PAD src0_sel:WORD_1
	v_pk_fma_f32 v[108:109], v[108:109], v[98:99], v[96:97] op_sel_hi:[0,1,1]
	v_cvt_pk_f16_f32 v113, v108, v109
	global_store_dwordx4 v[134:135], v[110:113], off
	s_branch .LBB0_641
